# planA v3: sample-unit publish moved to wave 7, concurrent with wave 0 group wait
# speedup vs baseline: 1.0026x; 1.0015x over previous
; #define PG8_WAIT_V(n) asm volatile("s_waitcnt vmcnt(" #n ")" ::: "memory")
; #define PG8_BAR __builtin_amdgcn_s_barrier()
; #define GRID_BAR() xcd_barrier(xbar)
; template <class Epi, class Sched, bool ALIGN_EPI = false, bool SP2 = false>
; __device__ __forceinline__ void gemm_phase(LAS unsigned char* lds, const Gemm g, const Sched& S, const Epi& E) {
;     ...
;     PG8_WAIT_V(0);
;     if constexpr (!ALIGN_EPI) { if (wr == 0) PG8_BAR; }
;     PG8_BAR;
; __global__ void __launch_bounds__(512, 2) fwd_megakernel(Params p) {
;     ...
;             GRID_BAR();
.LBB0_143:
	s_waitcnt vmcnt(0)
	s_waitcnt vmcnt(0) lgkmcnt(0)
	s_barrier
	s_cmpk_gt_u32 s65, 87
	s_cbranch_scc1 .Lpa_sa_done
	v_cmp_eq_u32_e32 vcc, 0x1c0, v216
	s_and_saveexec_b64 s[100:101], vcc
	s_cbranch_execz .Lpa_sa_skip
	buffer_wbl2 sc1
	v_readlane_b32 vcc_lo, v246, 29
	s_lshl_b32 vcc_lo, vcc_lo, 6
	s_add_u32 vcc_lo, vcc_lo, 0x83620
	v_mov_b32_e32 v2, vcc_lo
	v_mov_b32_e32 v4, 1
	s_waitcnt vmcnt(0)
	global_atomic_add v2, v4, s[98:99]

; #define GRID_BAR() xcd_barrier(xbar)
; __global__ void __launch_bounds__(512, 2) fwd_megakernel(Params p) {
;     ...
;             GRID_BAR();
.Lpa_sa_done:
	v_cmp_eq_u32_e32 vcc, 0, v216
	s_and_saveexec_b64 s[100:101], vcc
	s_cbranch_execz .Lpa_gw_done
	v_readlane_b32 vcc_lo, v246, 29
	s_lshl_b32 vcc_lo, vcc_lo, 6
	s_add_u32 vcc_lo, vcc_lo, 0x83600
	s_and_b32 vcc_hi, s65, 7
	s_lshl_b32 vcc_hi, vcc_hi, 2
	s_add_u32 vcc_lo, vcc_lo, vcc_hi
	v_mov_b32_e32 v2, vcc_lo
	s_mov_b32 vcc_hi, 0
